# attention softmax rewritten with plain f32 adds (no packed ops or moves); PV/QK LDS reads software-pipelined; P6 epilogue row-sums prefetched up front with cross-lane reduction; P8a epilogue loads pip
# speedup vs baseline: 1.0601x; 1.0601x over previous
.LBB0_716:
	s_and_saveexec_b64 s[30:31], s[4:5]
	s_xor_b64 s[30:31], exec, s[30:31]
	s_cbranch_execz .LBB0_718
	v_exp_f32_e32 v80, v80
	v_exp_f32_e32 v81, v81
	v_exp_f32_e32 v82, v82
	v_exp_f32_e32 v83, v83
	v_exp_f32_e32 v84, v84
	v_exp_f32_e32 v85, v85
	v_exp_f32_e32 v86, v86
	v_exp_f32_e32 v87, v87
	v_add_f32_e32 v2, v80, v84
	v_add_f32_e32 v3, v81, v85
	v_add_f32_e32 v4, v82, v86
	v_add_f32_e32 v5, v83, v87
	v_cvt_pk_bf16_f32 v128, v80, v81
	v_cvt_pk_bf16_f32 v129, v82, v83
	v_exp_f32_e32 v88, v88
	v_exp_f32_e32 v89, v89
	v_exp_f32_e32 v90, v90
	v_exp_f32_e32 v91, v91
	v_cvt_pk_bf16_f32 v130, v84, v85
	v_cvt_pk_bf16_f32 v131, v86, v87
	v_add_f32_e32 v2, v2, v88
	v_add_f32_e32 v3, v3, v89
	v_add_f32_e32 v4, v4, v90
	v_add_f32_e32 v5, v5, v91
	v_exp_f32_e32 v92, v92
	v_exp_f32_e32 v93, v93
	v_exp_f32_e32 v94, v94
	v_exp_f32_e32 v95, v95
	v_cvt_pk_bf16_f32 v132, v88, v89
	v_cvt_pk_bf16_f32 v133, v90, v91
	v_add_f32_e32 v2, v2, v92
	v_add_f32_e32 v3, v3, v93
	v_add_f32_e32 v4, v4, v94
	v_add_f32_e32 v5, v5, v95
	v_exp_f32_e32 v96, v96
	v_exp_f32_e32 v97, v97
	v_exp_f32_e32 v98, v98
	v_exp_f32_e32 v99, v99
	v_cvt_pk_bf16_f32 v134, v92, v93
	v_cvt_pk_bf16_f32 v135, v94, v95
	v_add_f32_e32 v2, v2, v96
	v_add_f32_e32 v3, v3, v97
	v_add_f32_e32 v4, v4, v98
	v_add_f32_e32 v5, v5, v99
	v_exp_f32_e32 v100, v100
	v_exp_f32_e32 v101, v101
	v_exp_f32_e32 v102, v102
	v_exp_f32_e32 v103, v103
	v_cvt_pk_bf16_f32 v136, v96, v97
	v_cvt_pk_bf16_f32 v137, v98, v99
	v_add_f32_e32 v2, v2, v100
	v_add_f32_e32 v3, v3, v101
	v_add_f32_e32 v4, v4, v102
	v_add_f32_e32 v5, v5, v103
	v_exp_f32_e32 v104, v104
	v_exp_f32_e32 v105, v105
	v_exp_f32_e32 v106, v106
	v_exp_f32_e32 v107, v107
	v_cvt_pk_bf16_f32 v138, v100, v101
	v_cvt_pk_bf16_f32 v139, v102, v103
	v_add_f32_e32 v2, v2, v104
	v_add_f32_e32 v3, v3, v105
	v_add_f32_e32 v4, v4, v106
	v_add_f32_e32 v5, v5, v107
	v_exp_f32_e32 v108, v108
	v_exp_f32_e32 v109, v109
	v_exp_f32_e32 v110, v110
	v_exp_f32_e32 v111, v111
	v_cvt_pk_bf16_f32 v140, v104, v105
	v_cvt_pk_bf16_f32 v141, v106, v107
	v_add_f32_e32 v2, v2, v108
	v_add_f32_e32 v3, v3, v109
	v_add_f32_e32 v4, v4, v110
	v_add_f32_e32 v5, v5, v111
	v_add_f32_e32 v2, v2, v3
	v_add_f32_e32 v4, v4, v5
	v_cvt_pk_bf16_f32 v142, v108, v109
	v_add_f32_e32 v2, v2, v4
	v_cvt_pk_bf16_f32 v143, v110, v111
	v_add_f32_e32 v165, v165, v2

.LBB0_723:
	v_add_u32_e32 v0, s96, v191
	v_add_u32_e32 v14, s96, v192
	v_add_u32_e32 v15, s96, v193
	v_add_u32_e32 v171, s96, v194
	v_add_u32_e32 v180, s96, v195
	v_add_u32_e32 v181, s96, v196
	v_add_u32_e32 v253, s96, v197
	v_add_u32_e32 v254, s96, v187
	v_add_u32_e32 v249, s93, v145
	v_add_u32_e32 v250, s93, v159
	v_add_u32_e32 v251, s93, v160
	v_add_u32_e32 v252, s93, v161
	ds_read_b64_tr_b16 v[2:3], v0 offset:49152
	ds_read_b64_tr_b16 v[4:5], v14 offset:49152
	ds_read_b64_tr_b16 v[6:7], v15 offset:49152
	ds_read_b64_tr_b16 v[8:9], v171 offset:49152
	ds_read_b64_tr_b16 v[10:11], v180 offset:49152
	ds_read_b64_tr_b16 v[12:13], v181 offset:49152
	ds_read_b64_tr_b16 v[172:173], v253 offset:49152
	ds_read_b64_tr_b16 v[174:175], v254 offset:49152
	ds_read_b64_tr_b16 v[198:199], v0 offset:53248
	ds_read_b64_tr_b16 v[200:201], v14 offset:53248
	ds_read_b64_tr_b16 v[202:203], v15 offset:53248
	ds_read_b64_tr_b16 v[204:205], v171 offset:53248
	ds_read_b64_tr_b16 v[206:207], v180 offset:53248
	ds_read_b64_tr_b16 v[208:209], v181 offset:53248
	s_setprio 2
	s_waitcnt lgkmcnt(12)
	v_mfma_f32_32x32x16_bf16 v[64:79], v[2:5], v[128:131], v[64:79]
	ds_read_b64_tr_b16 v[176:177], v253 offset:53248
	ds_read_b64_tr_b16 v[178:179], v254 offset:53248
	s_waitcnt lgkmcnt(12)
	v_mfma_f32_32x32x16_bf16 v[48:63], v[6:9], v[128:131], v[48:63]
	ds_read_b64_tr_b16 v[2:3], v0 offset:57344
	ds_read_b64_tr_b16 v[4:5], v14 offset:57344
	s_waitcnt lgkmcnt(12)
	v_mfma_f32_32x32x16_bf16 v[32:47], v[10:13], v[128:131], v[32:47]
	ds_read_b64_tr_b16 v[6:7], v15 offset:57344
	ds_read_b64_tr_b16 v[8:9], v171 offset:57344
	s_waitcnt lgkmcnt(12)
	v_mfma_f32_32x32x16_bf16 v[16:31], v[172:175], v[128:131], v[16:31]
	ds_read_b64_tr_b16 v[10:11], v180 offset:57344
	ds_read_b64_tr_b16 v[12:13], v181 offset:57344
	s_waitcnt lgkmcnt(12)
	v_mfma_f32_32x32x16_bf16 v[64:79], v[198:201], v[132:135], v[64:79]
	ds_read_b64_tr_b16 v[172:173], v253 offset:57344
	ds_read_b64_tr_b16 v[174:175], v254 offset:57344
	s_waitcnt lgkmcnt(12)
	v_mfma_f32_32x32x16_bf16 v[48:63], v[202:205], v[132:135], v[48:63]
	ds_read_b64_tr_b16 v[198:199], v0 offset:61440
	ds_read_b64_tr_b16 v[200:201], v14 offset:61440
	s_waitcnt lgkmcnt(12)
	v_mfma_f32_32x32x16_bf16 v[32:47], v[206:209], v[132:135], v[32:47]
	ds_read_b64_tr_b16 v[202:203], v15 offset:61440
	ds_read_b64_tr_b16 v[204:205], v171 offset:61440
	s_waitcnt lgkmcnt(12)
	v_mfma_f32_32x32x16_bf16 v[16:31], v[176:179], v[132:135], v[16:31]
	ds_read_b64_tr_b16 v[206:207], v180 offset:61440
	ds_read_b64_tr_b16 v[208:209], v181 offset:61440
	s_waitcnt lgkmcnt(12)
	v_mfma_f32_32x32x16_bf16 v[64:79], v[2:5], v[136:139], v[64:79]
	ds_read_b64_tr_b16 v[176:177], v253 offset:61440
	ds_read_b64_tr_b16 v[178:179], v254 offset:61440
	s_waitcnt lgkmcnt(12)
	v_mfma_f32_32x32x16_bf16 v[48:63], v[6:9], v[136:139], v[48:63]
	ds_read_b128 v[2:5], v249
	s_waitcnt lgkmcnt(11)
	v_mfma_f32_32x32x16_bf16 v[32:47], v[10:13], v[136:139], v[32:47]
	ds_read_b128 v[6:9], v249 offset:8192
	s_waitcnt lgkmcnt(10)
	v_mfma_f32_32x32x16_bf16 v[16:31], v[172:175], v[136:139], v[16:31]
	ds_read_b128 v[10:13], v250
	s_waitcnt lgkmcnt(9)
	v_mfma_f32_32x32x16_bf16 v[64:79], v[198:201], v[140:143], v[64:79]
	ds_read_b128 v[172:175], v250 offset:8192
	s_waitcnt lgkmcnt(8)
	v_mfma_f32_32x32x16_bf16 v[48:63], v[202:205], v[140:143], v[48:63]
	ds_read_b128 v[198:201], v251
	s_waitcnt lgkmcnt(7)
	v_mfma_f32_32x32x16_bf16 v[32:47], v[206:209], v[140:143], v[32:47]
	ds_read_b128 v[202:205], v251 offset:8192
	s_waitcnt lgkmcnt(6)
	v_mfma_f32_32x32x16_bf16 v[16:31], v[176:179], v[140:143], v[16:31]
	ds_read_b128 v[206:209], v252
	ds_read_b128 v[176:179], v252 offset:8192
	s_cmp_ge_i32 s95, s87
	s_cbranch_scc1 .Lc1_noqk
	s_waitcnt lgkmcnt(7)
	v_mfma_f32_32x32x16_bf16 v[80:95], v[2:5], v[112:115], 0
	s_waitcnt lgkmcnt(6)
	v_mfma_f32_32x32x16_bf16 v[96:111], v[6:9], v[112:115], 0
	s_waitcnt lgkmcnt(5)
	v_mfma_f32_32x32x16_bf16 v[80:95], v[10:13], v[116:119], v[80:95]
	s_waitcnt lgkmcnt(4)
	v_mfma_f32_32x32x16_bf16 v[96:111], v[172:175], v[116:119], v[96:111]
	s_waitcnt lgkmcnt(3)
	v_mfma_f32_32x32x16_bf16 v[80:95], v[198:201], v[120:123], v[80:95]
	s_waitcnt lgkmcnt(2)
	v_mfma_f32_32x32x16_bf16 v[96:111], v[202:205], v[120:123], v[96:111]
	s_waitcnt lgkmcnt(1)
	v_mfma_f32_32x32x16_bf16 v[80:95], v[206:209], v[124:127], v[80:95]
	s_waitcnt lgkmcnt(0)
	v_mfma_f32_32x32x16_bf16 v[96:111], v[176:179], v[124:127], v[96:111]
	s_setprio 1
	s_branch .Lc1_postqk
.Lc1_noqk:
	s_setprio 1
	s_branch .LBB0_711

; #define ATT_BAR() do { asm volatile("s_waitcnt lgkmcnt(0)" ::: "memory"); __builtin_amdgcn_s_barrier(); asm volatile("" ::: "memory"); } while (0)
; #define ATT_EVEN(j_, k2_, v1_) do { if (!F32) { if ((j_) + 2 < nt) ATT_DMAK((j_) + 2, k2_); if ((j_) + 1 < nt) ATT_DMAV((j_) + 1, v1_); } } while (0)
; template <bool F32>
; __device__ __forceinline__ void attn_unit(const AUnit& U, LAS unsigned char* lds, float lam, const float* subg) {
;     ...
;         for (int it = 0; it <= nt; ++it) {
;             ATT_EVEN(it, r0, r2);
;             if (it >= 1 && it <= mnt) ATT_SM(it - 1);
;             ATT_MM((it >= 1 && it <= mnt), (it < mnt), r0, r1);
;             ATT_ODD(it, r2, r1);
;             ATT_BAR();
;             { const int t_ = r0; r0 = r1; r1 = r2; r2 = t_; }
.Lc1_postqk:
	s_mov_b64 s[28:29], -1
	s_and_b64 vcc, exec, s[24:25]
	s_cbranch_vccz .LBB0_712

.LBB0_747:
	v_add_u32_e32 v0, s92, v191
	v_add_u32_e32 v14, s92, v192
	v_add_u32_e32 v15, s92, v193
	v_add_u32_e32 v171, s92, v194
	v_add_u32_e32 v180, s92, v195
	v_add_u32_e32 v181, s92, v196
	v_add_u32_e32 v253, s92, v197
	v_add_u32_e32 v254, s92, v187
	v_add_u32_e32 v249, s29, v145
	v_add_u32_e32 v250, s29, v159
	v_add_u32_e32 v251, s29, v160
	v_add_u32_e32 v252, s29, v161
	ds_read_b64_tr_b16 v[2:3], v0 offset:49152
	ds_read_b64_tr_b16 v[4:5], v14 offset:49152
	ds_read_b64_tr_b16 v[6:7], v15 offset:49152
	ds_read_b64_tr_b16 v[8:9], v171 offset:49152
	ds_read_b64_tr_b16 v[10:11], v180 offset:49152
	ds_read_b64_tr_b16 v[12:13], v181 offset:49152
	ds_read_b64_tr_b16 v[172:173], v253 offset:49152
	ds_read_b64_tr_b16 v[174:175], v254 offset:49152
	ds_read_b64_tr_b16 v[198:199], v0 offset:53248
	ds_read_b64_tr_b16 v[200:201], v14 offset:53248
	ds_read_b64_tr_b16 v[202:203], v15 offset:53248
	ds_read_b64_tr_b16 v[204:205], v171 offset:53248
	ds_read_b64_tr_b16 v[206:207], v180 offset:53248
	ds_read_b64_tr_b16 v[208:209], v181 offset:53248
	s_setprio 2
	s_waitcnt lgkmcnt(12)
	v_mfma_f32_32x32x16_bf16 v[64:79], v[2:5], v[128:131], v[64:79]
	ds_read_b64_tr_b16 v[176:177], v253 offset:53248
	ds_read_b64_tr_b16 v[178:179], v254 offset:53248
	s_waitcnt lgkmcnt(12)
	v_mfma_f32_32x32x16_bf16 v[48:63], v[6:9], v[128:131], v[48:63]
	ds_read_b64_tr_b16 v[2:3], v0 offset:57344
	ds_read_b64_tr_b16 v[4:5], v14 offset:57344
	s_waitcnt lgkmcnt(12)
	v_mfma_f32_32x32x16_bf16 v[32:47], v[10:13], v[128:131], v[32:47]
	ds_read_b64_tr_b16 v[6:7], v15 offset:57344
	ds_read_b64_tr_b16 v[8:9], v171 offset:57344
	s_waitcnt lgkmcnt(12)
	v_mfma_f32_32x32x16_bf16 v[16:31], v[172:175], v[128:131], v[16:31]
	ds_read_b64_tr_b16 v[10:11], v180 offset:57344
	ds_read_b64_tr_b16 v[12:13], v181 offset:57344
	s_waitcnt lgkmcnt(12)
	v_mfma_f32_32x32x16_bf16 v[64:79], v[198:201], v[132:135], v[64:79]
	ds_read_b64_tr_b16 v[172:173], v253 offset:57344
	ds_read_b64_tr_b16 v[174:175], v254 offset:57344
	s_waitcnt lgkmcnt(12)
	v_mfma_f32_32x32x16_bf16 v[48:63], v[202:205], v[132:135], v[48:63]
	ds_read_b64_tr_b16 v[198:199], v0 offset:61440
	ds_read_b64_tr_b16 v[200:201], v14 offset:61440
	s_waitcnt lgkmcnt(12)
	v_mfma_f32_32x32x16_bf16 v[32:47], v[206:209], v[132:135], v[32:47]
	ds_read_b64_tr_b16 v[202:203], v15 offset:61440
	ds_read_b64_tr_b16 v[204:205], v171 offset:61440
	s_waitcnt lgkmcnt(12)
	v_mfma_f32_32x32x16_bf16 v[16:31], v[176:179], v[132:135], v[16:31]
	ds_read_b64_tr_b16 v[206:207], v180 offset:61440
	ds_read_b64_tr_b16 v[208:209], v181 offset:61440
	s_waitcnt lgkmcnt(12)
	v_mfma_f32_32x32x16_bf16 v[64:79], v[2:5], v[136:139], v[64:79]
	ds_read_b64_tr_b16 v[176:177], v253 offset:61440
	ds_read_b64_tr_b16 v[178:179], v254 offset:61440
	s_waitcnt lgkmcnt(12)
	v_mfma_f32_32x32x16_bf16 v[48:63], v[6:9], v[136:139], v[48:63]
	ds_read_b128 v[2:5], v249
	s_waitcnt lgkmcnt(11)
	v_mfma_f32_32x32x16_bf16 v[32:47], v[10:13], v[136:139], v[32:47]
	ds_read_b128 v[6:9], v249 offset:8192
	s_waitcnt lgkmcnt(10)
	v_mfma_f32_32x32x16_bf16 v[16:31], v[172:175], v[136:139], v[16:31]
	ds_read_b128 v[10:13], v250
	s_waitcnt lgkmcnt(9)
	v_mfma_f32_32x32x16_bf16 v[64:79], v[198:201], v[140:143], v[64:79]
	ds_read_b128 v[172:175], v250 offset:8192
	s_waitcnt lgkmcnt(8)
	v_mfma_f32_32x32x16_bf16 v[48:63], v[202:205], v[140:143], v[48:63]
	ds_read_b128 v[198:201], v251
	s_waitcnt lgkmcnt(7)
	v_mfma_f32_32x32x16_bf16 v[32:47], v[206:209], v[140:143], v[32:47]
	ds_read_b128 v[202:205], v251 offset:8192
	s_waitcnt lgkmcnt(6)
	v_mfma_f32_32x32x16_bf16 v[16:31], v[176:179], v[140:143], v[16:31]
	ds_read_b128 v[206:209], v252
	ds_read_b128 v[176:179], v252 offset:8192
	s_cmp_lt_i32 s31, s87
	s_cselect_b64 s[26:27], -1, 0
	s_cmp_ge_i32 s31, s87
	s_cbranch_scc1 .Lc0_noqk
	s_waitcnt lgkmcnt(7)
	v_mfma_f32_32x32x16_bf16 v[80:95], v[2:5], v[112:115], 0
	s_waitcnt lgkmcnt(6)
	v_mfma_f32_32x32x16_bf16 v[96:111], v[6:9], v[112:115], 0
	s_waitcnt lgkmcnt(5)
	v_mfma_f32_32x32x16_bf16 v[80:95], v[10:13], v[116:119], v[80:95]
	s_waitcnt lgkmcnt(4)
	v_mfma_f32_32x32x16_bf16 v[96:111], v[172:175], v[116:119], v[96:111]
	s_waitcnt lgkmcnt(3)
	v_mfma_f32_32x32x16_bf16 v[80:95], v[198:201], v[120:123], v[80:95]
	s_waitcnt lgkmcnt(2)
	v_mfma_f32_32x32x16_bf16 v[96:111], v[202:205], v[120:123], v[96:111]
	s_waitcnt lgkmcnt(1)
	v_mfma_f32_32x32x16_bf16 v[80:95], v[206:209], v[124:127], v[80:95]
	s_waitcnt lgkmcnt(0)
	v_mfma_f32_32x32x16_bf16 v[96:111], v[176:179], v[124:127], v[96:111]
	s_setprio 0
	s_branch .LBB0_749
.Lc0_noqk:
	s_setprio 0
	s_branch .LBB0_741

.LBB0_749:
	s_and_saveexec_b64 s[26:27], s[4:5]
	s_xor_b64 s[26:27], exec, s[26:27]
	s_cbranch_execz .LBB0_751
	s_nop 3
	v_exp_f32_e32 v80, v80
	v_exp_f32_e32 v81, v81
	v_exp_f32_e32 v82, v82
	v_exp_f32_e32 v83, v83
	v_exp_f32_e32 v84, v84
	v_exp_f32_e32 v85, v85
	v_exp_f32_e32 v86, v86
	v_exp_f32_e32 v87, v87
	v_add_f32_e32 v2, v80, v84
	v_add_f32_e32 v3, v81, v85
	v_add_f32_e32 v4, v82, v86
	v_add_f32_e32 v5, v83, v87
	v_cvt_pk_bf16_f32 v128, v80, v81
	v_cvt_pk_bf16_f32 v129, v82, v83
	v_exp_f32_e32 v88, v88
	v_exp_f32_e32 v89, v89
	v_exp_f32_e32 v90, v90
	v_exp_f32_e32 v91, v91
	v_cvt_pk_bf16_f32 v130, v84, v85
	v_cvt_pk_bf16_f32 v131, v86, v87
	v_add_f32_e32 v2, v2, v88
	v_add_f32_e32 v3, v3, v89
	v_add_f32_e32 v4, v4, v90
	v_add_f32_e32 v5, v5, v91
	v_exp_f32_e32 v92, v92
	v_exp_f32_e32 v93, v93
	v_exp_f32_e32 v94, v94
	v_exp_f32_e32 v95, v95
	v_cvt_pk_bf16_f32 v132, v88, v89
	v_cvt_pk_bf16_f32 v133, v90, v91
	v_add_f32_e32 v2, v2, v92
	v_add_f32_e32 v3, v3, v93
	v_add_f32_e32 v4, v4, v94
	v_add_f32_e32 v5, v5, v95
	v_exp_f32_e32 v96, v96
	v_exp_f32_e32 v97, v97
	v_exp_f32_e32 v98, v98
	v_exp_f32_e32 v99, v99
	v_cvt_pk_bf16_f32 v134, v92, v93
	v_cvt_pk_bf16_f32 v135, v94, v95
	v_add_f32_e32 v2, v2, v96
	v_add_f32_e32 v3, v3, v97
	v_add_f32_e32 v4, v4, v98
	v_add_f32_e32 v5, v5, v99
	v_exp_f32_e32 v100, v100
	v_exp_f32_e32 v101, v101
	v_exp_f32_e32 v102, v102
	v_exp_f32_e32 v103, v103
	v_cvt_pk_bf16_f32 v136, v96, v97
	v_cvt_pk_bf16_f32 v137, v98, v99
	v_add_f32_e32 v2, v2, v100
	v_add_f32_e32 v3, v3, v101
	v_add_f32_e32 v4, v4, v102
	v_add_f32_e32 v5, v5, v103
	v_exp_f32_e32 v104, v104
	v_exp_f32_e32 v105, v105
	v_exp_f32_e32 v106, v106
	v_exp_f32_e32 v107, v107
	v_cvt_pk_bf16_f32 v138, v100, v101
	v_cvt_pk_bf16_f32 v139, v102, v103
	v_add_f32_e32 v2, v2, v104
	v_add_f32_e32 v3, v3, v105
	v_add_f32_e32 v4, v4, v106
	v_add_f32_e32 v5, v5, v107
	v_exp_f32_e32 v108, v108
	v_exp_f32_e32 v109, v109
	v_exp_f32_e32 v110, v110
	v_exp_f32_e32 v111, v111
	v_cvt_pk_bf16_f32 v140, v104, v105
	v_cvt_pk_bf16_f32 v141, v106, v107
	v_add_f32_e32 v2, v2, v108
	v_add_f32_e32 v3, v3, v109
	v_add_f32_e32 v4, v4, v110
	v_add_f32_e32 v5, v5, v111
	v_add_f32_e32 v2, v2, v3
	v_add_f32_e32 v4, v4, v5
	v_cvt_pk_bf16_f32 v142, v108, v109
	v_add_f32_e32 v2, v2, v4
	v_cvt_pk_bf16_f32 v143, v110, v111
	v_add_f32_e32 v165, v165, v2

;     __device__ __forceinline__ void operator()(const Acc& acc, const Unit& u, int wr, int wc, int fr, int fq) const {
;     ...
;             for (int m = 0; m < 4; ++m) { const int row = row0 + ai * HALF + m * 16; const size_t ro = (size_t)row * DFF + col0;
;                 float rsum = 0.f;
; #pragma unroll
;                 for (int q = 0; q < 8; ++q) { const f32x4 pv = *(const f32x4*)(rss + (size_t)row * 32 + 4 * q); rsum += (pv[0] + pv[1]) + (pv[2] + pv[3]); }
;                 const float rs = rsqrtf(rsum * (1.0f / (float)D) + EPS);
.LBB0_1471:
	s_lshl_b32 s23, s34, 8
	s_add_i32 s23, s23, s51
	v_or_b32_e32 v176, s23, v163
	v_ashrrev_i32_e32 v177, 31, v176
	v_lshlrev_b64 v[128:129], 7, v[176:177]
	v_lshl_add_u64 v[140:141], s[0:1], 0, v[128:129]
	v_lshlrev_b32_e32 v234, 1, v162
	v_and_b32_e32 v234, 0x60, v234
	v_mov_b32_e32 v235, 0
	v_lshl_add_u64 v[230:231], v[140:141], 0, v[234:235]
	global_load_dwordx4 v[128:131], v[230:231], off
	global_load_dwordx4 v[132:135], v[230:231], off offset:16
	global_load_dwordx4 v[136:139], v[230:231], off offset:2048
	global_load_dwordx4 v[140:143], v[230:231], off offset:2064
	s_mov_b64 vcc, 0x1000
	v_lshl_add_u64 v[230:231], v[230:231], 0, vcc
	global_load_dwordx4 v[144:147], v[230:231], off
	global_load_dwordx4 v[148:151], v[230:231], off offset:16
	global_load_dwordx4 v[152:155], v[230:231], off offset:2048
	global_load_dwordx4 v[156:159], v[230:231], off offset:2064
	s_mov_b64 vcc, 0x3000
	v_lshl_add_u64 v[230:231], v[230:231], 0, vcc
	global_load_dwordx4 v[198:201], v[230:231], off
	global_load_dwordx4 v[202:205], v[230:231], off offset:16
	global_load_dwordx4 v[206:209], v[230:231], off offset:2048
	global_load_dwordx4 v[210:213], v[230:231], off offset:2064
	s_mov_b64 vcc, 0x1000
	v_lshl_add_u64 v[230:231], v[230:231], 0, vcc
	global_load_dwordx4 v[214:217], v[230:231], off
	global_load_dwordx4 v[218:221], v[230:231], off offset:16
	global_load_dwordx4 v[222:225], v[230:231], off offset:2048
	global_load_dwordx4 v[226:229], v[230:231], off offset:2064
	v_lshl_or_b32 v174, s30, 7, v191
	v_ashrrev_i32_e32 v175, 31, v174
	v_cmp_lt_i32_e32 vcc, s62, v176
	v_mov_b64_e32 v[178:179], 0
	s_and_saveexec_b64 s[30:31], vcc
	s_cbranch_execz .LBB0_1478
	s_cmpk_gt_u32 s23, 0x3fff
	s_mov_b64 s[34:35], -1
	s_cbranch_scc0 .LBB0_1476
	v_mov_b64_e32 v[178:179], 0
	s_and_saveexec_b64 s[34:35], s[4:5]
	s_add_i32 s25, s23, 0xffffc000
	s_lshr_b32 s25, s25, 3
	v_add_u32_e32 v177, s25, v189
	v_mov_b64_e32 v[178:179], s[10:11]
	v_mad_u64_u32 v[178:179], s[36:37], v177, s64, v[178:179]
	v_lshl_add_u64 v[178:179], v[174:175], 2, v[178:179]
	s_or_b64 exec, exec, s[34:35]
	s_mov_b64 s[34:35], 0

; __device__ __forceinline__ unsigned cvt_pk_bf16(float lo, float hi) { f32x2 v = {lo, hi}; bf16x2_t b = __builtin_convertvector(v, bf16x2_t); return __builtin_bit_cast(unsigned, b); }
;     __device__ __forceinline__ void operator()(const Acc& acc, const Unit& u, int wr, int wc, int fr, int fq) const {
;     ...
;                 float rsum = 0.f;
; #pragma unroll
;                 for (int q = 0; q < 8; ++q) { const f32x4 pv = *(const f32x4*)(rss + (size_t)row * 32 + 4 * q); rsum += (pv[0] + pv[1]) + (pv[2] + pv[3]); }
;                 const float rs = rsqrtf(rsum * (1.0f / (float)D) + EPS);
;                 float* co = nullptr;
;                 if (row >= MP - 2) { if (row < MP) co = out + O_CP + (size_t)(row - (MP - 2)) * DFF + col0;
;                                      else { const int t = (row - MP) & 15, b = (row - MP) >> 4; if (t >= 14) co = out + O_CS + (size_t)(b * 2 + t - 14) * DFF + col0; } }
; #pragma unroll
;                 for (int n = 0; n < 2; ++n) { const f32x4 z = acc[ai][0][m][n] * rs, v = acc[ai][1][m][n] * rs;
;                     u32x2 w; w.x = cvt_pk_bf16(z[0], z[1]); w.y = cvt_pk_bf16(z[2], z[3]); *(u32x2*)(Z + ro + 16 * n) = w;
;                     w.x = cvt_pk_bf16(v[0], v[1]); w.y = cvt_pk_bf16(v[2], v[3]); *(u32x2*)(VAL + ro + 16 * n) = w;
;                     if (co) *(f32x4*)(co + 16 * n) = z; } }
.LBB0_1478:
	s_or_b64 exec, exec, s[30:31]
	s_waitcnt vmcnt(8)
	v_add_f32_e32 v128, v128, v129
	v_add_f32_e32 v130, v130, v131
	v_add_f32_e32 v132, v132, v133
	v_add_f32_e32 v134, v134, v135
	v_add_f32_e32 v136, v136, v137
	v_add_f32_e32 v138, v138, v139
	v_add_f32_e32 v140, v140, v141
	v_add_f32_e32 v142, v142, v143
	v_add_f32_e32 v144, v144, v145
	v_add_f32_e32 v146, v146, v147
	v_add_f32_e32 v148, v148, v149
	v_add_f32_e32 v150, v150, v151
	v_add_f32_e32 v152, v152, v153
	v_add_f32_e32 v154, v154, v155
	v_add_f32_e32 v156, v156, v157
	v_add_f32_e32 v158, v158, v159
	v_add_f32_e32 v128, v128, v130
	v_add_f32_e32 v132, v132, v134
	v_add_f32_e32 v136, v136, v138
	v_add_f32_e32 v140, v140, v142
	v_add_f32_e32 v144, v144, v146
	v_add_f32_e32 v148, v148, v150
	v_add_f32_e32 v152, v152, v154
	v_add_f32_e32 v156, v156, v158
	v_add_f32_e32 v240, v128, v132
	v_add_f32_e32 v241, v136, v140
	v_add_f32_e32 v242, v144, v148
	v_add_f32_e32 v243, v152, v156
	s_waitcnt vmcnt(0)
	v_add_f32_e32 v198, v198, v199
	v_add_f32_e32 v200, v200, v201
	v_add_f32_e32 v202, v202, v203
	v_add_f32_e32 v204, v204, v205
	v_add_f32_e32 v206, v206, v207
	v_add_f32_e32 v208, v208, v209
	v_add_f32_e32 v210, v210, v211
	v_add_f32_e32 v212, v212, v213
	v_add_f32_e32 v214, v214, v215
	v_add_f32_e32 v216, v216, v217
	v_add_f32_e32 v218, v218, v219
	v_add_f32_e32 v220, v220, v221
	v_add_f32_e32 v222, v222, v223
	v_add_f32_e32 v224, v224, v225
	v_add_f32_e32 v226, v226, v227
	v_add_f32_e32 v228, v228, v229
	v_add_f32_e32 v198, v198, v200
	v_add_f32_e32 v202, v202, v204
	v_add_f32_e32 v206, v206, v208
	v_add_f32_e32 v210, v210, v212
	v_add_f32_e32 v214, v214, v216
	v_add_f32_e32 v218, v218, v220
	v_add_f32_e32 v222, v222, v224
	v_add_f32_e32 v226, v226, v228
	v_add_f32_e32 v244, v198, v202
	v_add_f32_e32 v245, v206, v210
	v_add_f32_e32 v246, v214, v218
	v_add_f32_e32 v247, v222, v226
	v_mov_b32_e32 v230, v240
	v_mov_b32_e32 v231, v241
	v_mov_b32_e32 v234, v242
	v_mov_b32_e32 v235, v243
	v_mov_b32_e32 v236, v244
	v_mov_b32_e32 v237, v245
	v_mov_b32_e32 v238, v246
	v_mov_b32_e32 v239, v247
	s_nop 1
	v_permlane16_swap_b32_e32 v240, v230
	v_permlane16_swap_b32_e32 v241, v231
	v_permlane16_swap_b32_e32 v242, v234
	v_permlane16_swap_b32_e32 v243, v235
	v_permlane16_swap_b32_e32 v244, v236
	v_permlane16_swap_b32_e32 v245, v237
	v_permlane16_swap_b32_e32 v246, v238
	v_permlane16_swap_b32_e32 v247, v239
	v_add_f32_e32 v240, v240, v230
	v_add_f32_e32 v241, v241, v231
	v_add_f32_e32 v242, v242, v234
	v_add_f32_e32 v243, v243, v235
	v_add_f32_e32 v244, v244, v236
	v_add_f32_e32 v245, v245, v237
	v_add_f32_e32 v246, v246, v238
	v_add_f32_e32 v247, v247, v239
	v_mov_b32_e32 v230, v240
	v_mov_b32_e32 v231, v241
	v_mov_b32_e32 v234, v242
	v_mov_b32_e32 v235, v243
	v_mov_b32_e32 v236, v244
	v_mov_b32_e32 v237, v245
	v_mov_b32_e32 v238, v246
	v_mov_b32_e32 v239, v247
	s_nop 1
	v_permlane32_swap_b32_e32 v240, v230
	v_permlane32_swap_b32_e32 v241, v231
	v_permlane32_swap_b32_e32 v242, v234
	v_permlane32_swap_b32_e32 v243, v235
	v_permlane32_swap_b32_e32 v244, v236
	v_permlane32_swap_b32_e32 v245, v237
	v_permlane32_swap_b32_e32 v246, v238
	v_permlane32_swap_b32_e32 v247, v239
	v_add_f32_e32 v240, v240, v230
	v_add_f32_e32 v241, v241, v231
	v_add_f32_e32 v242, v242, v234
	v_add_f32_e32 v243, v243, v235
	v_add_f32_e32 v244, v244, v236
	v_add_f32_e32 v245, v245, v237
	v_add_f32_e32 v246, v246, v238
	v_add_f32_e32 v247, v247, v239
	v_mad_i64_i32 v[130:131], s[30:31], v176, s65, v[174:175]
	v_mov_b32_e32 v128, v240
	v_fmamk_f32 v128, v128, 0x3a000000, v195
	v_mul_f32_e32 v129, 0x4b800000, v128
	v_cmp_gt_f32_e32 vcc, s66, v128
	v_lshlrev_b64 v[130:131], 1, v[130:131]
	s_nop 0
	v_cndmask_b32_e32 v128, v128, v129, vcc
	v_rsq_f32_e32 v128, v128
	s_nop 0
	v_mul_f32_e32 v129, 0x45800000, v128
	v_cndmask_b32_e32 v128, v128, v129, vcc
	v_pk_mul_f32 v[126:127], v[126:127], v[128:129] op_sel_hi:[1,0]
	v_pk_mul_f32 v[124:125], v[124:125], v[128:129] op_sel_hi:[1,0]
	v_pk_mul_f32 v[122:123], v[122:123], v[128:129] op_sel_hi:[1,0]
	v_pk_mul_f32 v[132:133], v[120:121], v[128:129] op_sel_hi:[1,0]
	v_cmp_ne_u64_e32 vcc, 0, v[178:179]
	v_cvt_pk_bf16_f32 v134, v124, v125
	v_cvt_pk_bf16_f32 v135, v126, v127
	v_lshl_add_u64 v[120:121], s[88:89], 0, v[130:131]
	v_cvt_pk_bf16_f32 v132, v132, v133
	v_cvt_pk_bf16_f32 v133, v122, v123
	v_lshl_add_u64 v[122:123], s[12:13], 0, v[130:131]
	global_store_dwordx2 v[120:121], v[134:135], off
	global_store_dwordx2 v[122:123], v[132:133], off
	s_and_saveexec_b64 s[30:31], vcc
	s_cbranch_execz .LBB0_1480
	global_store_dwordx4 v[178:179], v[124:127], off

;     __device__ __forceinline__ void operator()(const Acc& acc, const Unit& u, int wr, int wc, int fr, int fq) const {
;     ...
;             for (int m = 0; m < 4; ++m) { const int row = row0 + ai * HALF + m * 16; const size_t ro = (size_t)row * DFF + col0;
;                 float rsum = 0.f;
; #pragma unroll
;                 for (int q = 0; q < 8; ++q) { const f32x4 pv = *(const f32x4*)(rss + (size_t)row * 32 + 4 * q); rsum += (pv[0] + pv[1]) + (pv[2] + pv[3]); }
;                 const float rs = rsqrtf(rsum * (1.0f / (float)D) + EPS);
.LBB0_1482:
	s_or_b64 exec, exec, s[30:31]
	v_or_b32_e32 v146, 16, v176
	v_ashrrev_i32_e32 v147, 31, v146
	v_lshlrev_b64 v[112:113], 7, v[146:147]
	v_lshl_add_u64 v[124:125], s[0:1], 0, v[112:113]
	v_cmp_lt_i32_e32 vcc, s62, v146
	v_mov_b64_e32 v[144:145], 0
	s_and_saveexec_b64 s[30:31], vcc
	s_cbranch_execz .LBB0_1489
	s_cmpk_lt_u32 s23, 0x4000
	s_mov_b64 s[34:35], -1
	s_cbranch_scc1 .LBB0_1487
	v_mov_b64_e32 v[144:145], 0
	s_and_saveexec_b64 s[34:35], s[4:5]
	s_add_i32 s25, s23, 0xffffc010
	s_lshr_b32 s25, s25, 3
	v_add_u32_e32 v147, s25, v189
	v_mov_b64_e32 v[144:145], s[10:11]
	v_mad_u64_u32 v[144:145], s[36:37], v147, s64, v[144:145]
	v_lshl_add_u64 v[144:145], v[174:175], 2, v[144:145]
	s_or_b64 exec, exec, s[34:35]
	s_mov_b64 s[34:35], 0

; __device__ __forceinline__ unsigned cvt_pk_bf16(float lo, float hi) { f32x2 v = {lo, hi}; bf16x2_t b = __builtin_convertvector(v, bf16x2_t); return __builtin_bit_cast(unsigned, b); }
;     __device__ __forceinline__ void operator()(const Acc& acc, const Unit& u, int wr, int wc, int fr, int fq) const {
;     ...
;                 float rsum = 0.f;
; #pragma unroll
;                 for (int q = 0; q < 8; ++q) { const f32x4 pv = *(const f32x4*)(rss + (size_t)row * 32 + 4 * q); rsum += (pv[0] + pv[1]) + (pv[2] + pv[3]); }
;                 const float rs = rsqrtf(rsum * (1.0f / (float)D) + EPS);
;                 float* co = nullptr;
;                 if (row >= MP - 2) { if (row < MP) co = out + O_CP + (size_t)(row - (MP - 2)) * DFF + col0;
;                                      else { const int t = (row - MP) & 15, b = (row - MP) >> 4; if (t >= 14) co = out + O_CS + (size_t)(b * 2 + t - 14) * DFF + col0; } }
; #pragma unroll
;                 for (int n = 0; n < 2; ++n) { const f32x4 z = acc[ai][0][m][n] * rs, v = acc[ai][1][m][n] * rs;
;                     u32x2 w; w.x = cvt_pk_bf16(z[0], z[1]); w.y = cvt_pk_bf16(z[2], z[3]); *(u32x2*)(Z + ro + 16 * n) = w;
;                     w.x = cvt_pk_bf16(v[0], v[1]); w.y = cvt_pk_bf16(v[2], v[3]); *(u32x2*)(VAL + ro + 16 * n) = w;
;                     if (co) *(f32x4*)(co + 16 * n) = z; } }
.LBB0_1489:
	s_or_b64 exec, exec, s[30:31]
	v_mad_i64_i32 v[114:115], s[30:31], v146, s65, v[174:175]
	v_mov_b32_e32 v112, v241
	v_fmamk_f32 v112, v112, 0x3a000000, v195
	v_mul_f32_e32 v113, 0x4b800000, v112
	v_cmp_gt_f32_e32 vcc, s66, v112
	v_lshlrev_b64 v[114:115], 1, v[114:115]
	s_nop 0
	v_cndmask_b32_e32 v112, v112, v113, vcc
	v_rsq_f32_e32 v112, v112
	s_nop 0
	v_mul_f32_e32 v113, 0x45800000, v112
	v_cndmask_b32_e32 v112, v112, v113, vcc
	v_pk_mul_f32 v[110:111], v[110:111], v[112:113] op_sel_hi:[1,0]
	v_pk_mul_f32 v[108:109], v[108:109], v[112:113] op_sel_hi:[1,0]
	v_pk_mul_f32 v[106:107], v[106:107], v[112:113] op_sel_hi:[1,0]
	v_pk_mul_f32 v[116:117], v[104:105], v[112:113] op_sel_hi:[1,0]
	v_cmp_ne_u64_e32 vcc, 0, v[144:145]
	v_cvt_pk_bf16_f32 v118, v108, v109
	v_cvt_pk_bf16_f32 v119, v110, v111
	v_lshl_add_u64 v[104:105], s[88:89], 0, v[114:115]
	v_cvt_pk_bf16_f32 v116, v116, v117
	v_cvt_pk_bf16_f32 v117, v106, v107
	v_lshl_add_u64 v[106:107], s[12:13], 0, v[114:115]
	global_store_dwordx2 v[104:105], v[118:119], off
	global_store_dwordx2 v[106:107], v[116:117], off
	s_and_saveexec_b64 s[30:31], vcc
	s_cbranch_execz .LBB0_1491
	global_store_dwordx4 v[144:145], v[108:111], off

;     __device__ __forceinline__ void operator()(const Acc& acc, const Unit& u, int wr, int wc, int fr, int fq) const {
;     ...
;             for (int m = 0; m < 4; ++m) { const int row = row0 + ai * HALF + m * 16; const size_t ro = (size_t)row * DFF + col0;
;                 float rsum = 0.f;
; #pragma unroll
;                 for (int q = 0; q < 8; ++q) { const f32x4 pv = *(const f32x4*)(rss + (size_t)row * 32 + 4 * q); rsum += (pv[0] + pv[1]) + (pv[2] + pv[3]); }
;                 const float rs = rsqrtf(rsum * (1.0f / (float)D) + EPS);
.LBB0_1493:
	s_or_b64 exec, exec, s[30:31]
	v_or_b32_e32 v130, 32, v176
	v_ashrrev_i32_e32 v131, 31, v130
	v_lshlrev_b64 v[96:97], 7, v[130:131]
	v_lshl_add_u64 v[108:109], s[0:1], 0, v[96:97]
	v_cmp_lt_i32_e32 vcc, s62, v130
	v_mov_b64_e32 v[128:129], 0
	s_and_saveexec_b64 s[30:31], vcc
	s_cbranch_execz .LBB0_1500
	s_cmpk_lt_u32 s23, 0x4000
	s_mov_b64 s[34:35], -1
	s_cbranch_scc1 .LBB0_1498
	v_mov_b64_e32 v[128:129], 0
	s_and_saveexec_b64 s[34:35], s[4:5]
	s_add_i32 s25, s23, 0xffffc020
	s_lshr_b32 s25, s25, 3
	v_add_u32_e32 v131, s25, v189
	v_mov_b64_e32 v[128:129], s[10:11]
	v_mad_u64_u32 v[128:129], s[36:37], v131, s64, v[128:129]
	v_lshl_add_u64 v[128:129], v[174:175], 2, v[128:129]
	s_or_b64 exec, exec, s[34:35]
	s_mov_b64 s[34:35], 0

; __device__ __forceinline__ unsigned cvt_pk_bf16(float lo, float hi) { f32x2 v = {lo, hi}; bf16x2_t b = __builtin_convertvector(v, bf16x2_t); return __builtin_bit_cast(unsigned, b); }
;     __device__ __forceinline__ void operator()(const Acc& acc, const Unit& u, int wr, int wc, int fr, int fq) const {
;     ...
;                 float rsum = 0.f;
; #pragma unroll
;                 for (int q = 0; q < 8; ++q) { const f32x4 pv = *(const f32x4*)(rss + (size_t)row * 32 + 4 * q); rsum += (pv[0] + pv[1]) + (pv[2] + pv[3]); }
;                 const float rs = rsqrtf(rsum * (1.0f / (float)D) + EPS);
;                 float* co = nullptr;
;                 if (row >= MP - 2) { if (row < MP) co = out + O_CP + (size_t)(row - (MP - 2)) * DFF + col0;
;                                      else { const int t = (row - MP) & 15, b = (row - MP) >> 4; if (t >= 14) co = out + O_CS + (size_t)(b * 2 + t - 14) * DFF + col0; } }
; #pragma unroll
;                 for (int n = 0; n < 2; ++n) { const f32x4 z = acc[ai][0][m][n] * rs, v = acc[ai][1][m][n] * rs;
;                     u32x2 w; w.x = cvt_pk_bf16(z[0], z[1]); w.y = cvt_pk_bf16(z[2], z[3]); *(u32x2*)(Z + ro + 16 * n) = w;
;                     w.x = cvt_pk_bf16(v[0], v[1]); w.y = cvt_pk_bf16(v[2], v[3]); *(u32x2*)(VAL + ro + 16 * n) = w;
;                     if (co) *(f32x4*)(co + 16 * n) = z; } }
.LBB0_1500:
	s_or_b64 exec, exec, s[30:31]
	v_mad_i64_i32 v[98:99], s[30:31], v130, s65, v[174:175]
	v_mov_b32_e32 v96, v242
	v_fmamk_f32 v96, v96, 0x3a000000, v195
	v_mul_f32_e32 v97, 0x4b800000, v96
	v_cmp_gt_f32_e32 vcc, s66, v96
	v_lshlrev_b64 v[98:99], 1, v[98:99]
	s_nop 0
	v_cndmask_b32_e32 v96, v96, v97, vcc
	v_rsq_f32_e32 v96, v96
	s_nop 0
	v_mul_f32_e32 v97, 0x45800000, v96
	v_cndmask_b32_e32 v96, v96, v97, vcc
	v_pk_mul_f32 v[94:95], v[94:95], v[96:97] op_sel_hi:[1,0]
	v_pk_mul_f32 v[92:93], v[92:93], v[96:97] op_sel_hi:[1,0]
	v_pk_mul_f32 v[90:91], v[90:91], v[96:97] op_sel_hi:[1,0]
	v_pk_mul_f32 v[100:101], v[88:89], v[96:97] op_sel_hi:[1,0]
	v_cmp_ne_u64_e32 vcc, 0, v[128:129]
	v_cvt_pk_bf16_f32 v102, v92, v93
	v_cvt_pk_bf16_f32 v103, v94, v95
	v_lshl_add_u64 v[88:89], s[88:89], 0, v[98:99]
	v_cvt_pk_bf16_f32 v100, v100, v101
	v_cvt_pk_bf16_f32 v101, v90, v91
	v_lshl_add_u64 v[90:91], s[12:13], 0, v[98:99]
	global_store_dwordx2 v[88:89], v[102:103], off
	global_store_dwordx2 v[90:91], v[100:101], off
	s_and_saveexec_b64 s[30:31], vcc
	s_cbranch_execz .LBB0_1502
	global_store_dwordx4 v[128:129], v[92:95], off

;     __device__ __forceinline__ void operator()(const Acc& acc, const Unit& u, int wr, int wc, int fr, int fq) const {
;     ...
;             for (int m = 0; m < 4; ++m) { const int row = row0 + ai * HALF + m * 16; const size_t ro = (size_t)row * DFF + col0;
;                 float rsum = 0.f;
; #pragma unroll
;                 for (int q = 0; q < 8; ++q) { const f32x4 pv = *(const f32x4*)(rss + (size_t)row * 32 + 4 * q); rsum += (pv[0] + pv[1]) + (pv[2] + pv[3]); }
;                 const float rs = rsqrtf(rsum * (1.0f / (float)D) + EPS);
.LBB0_1504:
	s_or_b64 exec, exec, s[30:31]
	v_or_b32_e32 v114, 48, v176
	v_ashrrev_i32_e32 v115, 31, v114
	v_lshlrev_b64 v[80:81], 7, v[114:115]
	v_lshl_add_u64 v[92:93], s[0:1], 0, v[80:81]
	v_cmp_lt_i32_e32 vcc, s62, v114
	v_mov_b64_e32 v[112:113], 0
	s_and_saveexec_b64 s[30:31], vcc
	s_cbranch_execz .LBB0_1511
	s_cmpk_lt_u32 s23, 0x4000
	s_mov_b64 s[34:35], -1
	s_cbranch_scc1 .LBB0_1509
	v_mov_b64_e32 v[112:113], 0
	s_and_saveexec_b64 s[34:35], s[4:5]
	s_add_i32 s25, s23, 0xffffc030
	s_lshr_b32 s25, s25, 3
	v_add_u32_e32 v115, s25, v189
	v_mov_b64_e32 v[112:113], s[10:11]
	v_mad_u64_u32 v[112:113], s[36:37], v115, s64, v[112:113]
	v_lshl_add_u64 v[112:113], v[174:175], 2, v[112:113]
	s_or_b64 exec, exec, s[34:35]
	s_mov_b64 s[34:35], 0

; __device__ __forceinline__ unsigned cvt_pk_bf16(float lo, float hi) { f32x2 v = {lo, hi}; bf16x2_t b = __builtin_convertvector(v, bf16x2_t); return __builtin_bit_cast(unsigned, b); }
;     __device__ __forceinline__ void operator()(const Acc& acc, const Unit& u, int wr, int wc, int fr, int fq) const {
;     ...
;                 float rsum = 0.f;
; #pragma unroll
;                 for (int q = 0; q < 8; ++q) { const f32x4 pv = *(const f32x4*)(rss + (size_t)row * 32 + 4 * q); rsum += (pv[0] + pv[1]) + (pv[2] + pv[3]); }
;                 const float rs = rsqrtf(rsum * (1.0f / (float)D) + EPS);
;                 float* co = nullptr;
;                 if (row >= MP - 2) { if (row < MP) co = out + O_CP + (size_t)(row - (MP - 2)) * DFF + col0;
;                                      else { const int t = (row - MP) & 15, b = (row - MP) >> 4; if (t >= 14) co = out + O_CS + (size_t)(b * 2 + t - 14) * DFF + col0; } }
; #pragma unroll
;                 for (int n = 0; n < 2; ++n) { const f32x4 z = acc[ai][0][m][n] * rs, v = acc[ai][1][m][n] * rs;
;                     u32x2 w; w.x = cvt_pk_bf16(z[0], z[1]); w.y = cvt_pk_bf16(z[2], z[3]); *(u32x2*)(Z + ro + 16 * n) = w;
;                     w.x = cvt_pk_bf16(v[0], v[1]); w.y = cvt_pk_bf16(v[2], v[3]); *(u32x2*)(VAL + ro + 16 * n) = w;
;                     if (co) *(f32x4*)(co + 16 * n) = z; } }
.LBB0_1511:
	s_or_b64 exec, exec, s[30:31]
	v_mad_i64_i32 v[82:83], s[30:31], v114, s65, v[174:175]
	v_mov_b32_e32 v80, v243
	v_fmamk_f32 v80, v80, 0x3a000000, v195
	v_mul_f32_e32 v81, 0x4b800000, v80
	v_cmp_gt_f32_e32 vcc, s66, v80
	v_lshlrev_b64 v[82:83], 1, v[82:83]
	s_nop 0
	v_cndmask_b32_e32 v80, v80, v81, vcc
	v_rsq_f32_e32 v80, v80
	s_nop 0
	v_mul_f32_e32 v81, 0x45800000, v80
	v_cndmask_b32_e32 v80, v80, v81, vcc
	v_pk_mul_f32 v[78:79], v[78:79], v[80:81] op_sel_hi:[1,0]
	v_pk_mul_f32 v[76:77], v[76:77], v[80:81] op_sel_hi:[1,0]
	v_pk_mul_f32 v[74:75], v[74:75], v[80:81] op_sel_hi:[1,0]
	v_pk_mul_f32 v[84:85], v[72:73], v[80:81] op_sel_hi:[1,0]
	v_cmp_ne_u64_e32 vcc, 0, v[112:113]
	v_cvt_pk_bf16_f32 v86, v76, v77
	v_cvt_pk_bf16_f32 v87, v78, v79
	v_lshl_add_u64 v[72:73], s[88:89], 0, v[82:83]
	v_cvt_pk_bf16_f32 v84, v84, v85
	v_cvt_pk_bf16_f32 v85, v74, v75
	v_lshl_add_u64 v[74:75], s[12:13], 0, v[82:83]
	global_store_dwordx2 v[72:73], v[86:87], off
	global_store_dwordx2 v[74:75], v[84:85], off
	s_and_saveexec_b64 s[30:31], vcc
	s_cbranch_execz .LBB0_1513
	global_store_dwordx4 v[112:113], v[76:79], off

;     __device__ __forceinline__ void operator()(const Acc& acc, const Unit& u, int wr, int wc, int fr, int fq) const {
;     ...
;             for (int m = 0; m < 4; ++m) { const int row = row0 + ai * HALF + m * 16; const size_t ro = (size_t)row * DFF + col0;
;                 float rsum = 0.f;
; #pragma unroll
;                 for (int q = 0; q < 8; ++q) { const f32x4 pv = *(const f32x4*)(rss + (size_t)row * 32 + 4 * q); rsum += (pv[0] + pv[1]) + (pv[2] + pv[3]); }
;                 const float rs = rsqrtf(rsum * (1.0f / (float)D) + EPS);
.LBB0_1515:
	s_or_b64 exec, exec, s[30:31]
	v_add_u32_e32 v98, 0x80, v176
	v_ashrrev_i32_e32 v99, 31, v98
	v_lshlrev_b64 v[64:65], 7, v[98:99]
	v_lshl_add_u64 v[76:77], s[0:1], 0, v[64:65]
	v_cmp_lt_i32_e32 vcc, s67, v176
	v_mov_b64_e32 v[96:97], 0
	s_and_saveexec_b64 s[30:31], vcc
	s_cbranch_execz .LBB0_1523
	v_cmp_lt_u32_e32 vcc, s63, v98
	s_and_saveexec_b64 s[34:35], vcc
	s_xor_b64 s[34:35], exec, s[34:35]
	s_cbranch_execz .LBB0_1520
	v_mov_b64_e32 v[96:97], 0
	s_and_saveexec_b64 s[36:37], s[4:5]
	s_add_i32 s25, s23, 0xffffc080
	s_lshr_b32 s25, s25, 3
	v_add_u32_e32 v99, s25, v189
	v_mov_b64_e32 v[96:97], s[10:11]
	v_mad_u64_u32 v[96:97], s[38:39], v99, s64, v[96:97]
	v_lshl_add_u64 v[96:97], v[174:175], 2, v[96:97]
	s_or_b64 exec, exec, s[36:37]

; __device__ __forceinline__ unsigned cvt_pk_bf16(float lo, float hi) { f32x2 v = {lo, hi}; bf16x2_t b = __builtin_convertvector(v, bf16x2_t); return __builtin_bit_cast(unsigned, b); }
;     __device__ __forceinline__ void operator()(const Acc& acc, const Unit& u, int wr, int wc, int fr, int fq) const {
;     ...
;                 float rsum = 0.f;
; #pragma unroll
;                 for (int q = 0; q < 8; ++q) { const f32x4 pv = *(const f32x4*)(rss + (size_t)row * 32 + 4 * q); rsum += (pv[0] + pv[1]) + (pv[2] + pv[3]); }
;                 const float rs = rsqrtf(rsum * (1.0f / (float)D) + EPS);
;                 float* co = nullptr;
;                 if (row >= MP - 2) { if (row < MP) co = out + O_CP + (size_t)(row - (MP - 2)) * DFF + col0;
;                                      else { const int t = (row - MP) & 15, b = (row - MP) >> 4; if (t >= 14) co = out + O_CS + (size_t)(b * 2 + t - 14) * DFF + col0; } }
; #pragma unroll
;                 for (int n = 0; n < 2; ++n) { const f32x4 z = acc[ai][0][m][n] * rs, v = acc[ai][1][m][n] * rs;
;                     u32x2 w; w.x = cvt_pk_bf16(z[0], z[1]); w.y = cvt_pk_bf16(z[2], z[3]); *(u32x2*)(Z + ro + 16 * n) = w;
;                     w.x = cvt_pk_bf16(v[0], v[1]); w.y = cvt_pk_bf16(v[2], v[3]); *(u32x2*)(VAL + ro + 16 * n) = w;
;                     if (co) *(f32x4*)(co + 16 * n) = z; } }
.LBB0_1523:
	s_or_b64 exec, exec, s[30:31]
	v_mad_i64_i32 v[66:67], s[30:31], v98, s65, v[174:175]
	v_mov_b32_e32 v64, v244
	v_fmamk_f32 v64, v64, 0x3a000000, v195
	v_mul_f32_e32 v65, 0x4b800000, v64
	v_cmp_gt_f32_e32 vcc, s66, v64
	v_lshlrev_b64 v[66:67], 1, v[66:67]
	s_nop 0
	v_cndmask_b32_e32 v64, v64, v65, vcc
	v_rsq_f32_e32 v64, v64
	s_nop 0
	v_mul_f32_e32 v65, 0x45800000, v64
	v_cndmask_b32_e32 v64, v64, v65, vcc
	v_pk_mul_f32 v[62:63], v[62:63], v[64:65] op_sel_hi:[1,0]
	v_pk_mul_f32 v[60:61], v[60:61], v[64:65] op_sel_hi:[1,0]
	v_pk_mul_f32 v[58:59], v[58:59], v[64:65] op_sel_hi:[1,0]
	v_pk_mul_f32 v[68:69], v[56:57], v[64:65] op_sel_hi:[1,0]
	v_cmp_ne_u64_e32 vcc, 0, v[96:97]
	v_cvt_pk_bf16_f32 v70, v60, v61
	v_cvt_pk_bf16_f32 v71, v62, v63
	v_lshl_add_u64 v[56:57], s[88:89], 0, v[66:67]
	v_cvt_pk_bf16_f32 v68, v68, v69
	v_cvt_pk_bf16_f32 v69, v58, v59
	v_lshl_add_u64 v[58:59], s[12:13], 0, v[66:67]
	global_store_dwordx2 v[56:57], v[70:71], off
	global_store_dwordx2 v[58:59], v[68:69], off
	s_and_saveexec_b64 s[30:31], vcc
	s_cbranch_execz .LBB0_1525
	global_store_dwordx4 v[96:97], v[60:63], off

;     __device__ __forceinline__ void operator()(const Acc& acc, const Unit& u, int wr, int wc, int fr, int fq) const {
;     ...
;             for (int m = 0; m < 4; ++m) { const int row = row0 + ai * HALF + m * 16; const size_t ro = (size_t)row * DFF + col0;
;                 float rsum = 0.f;
; #pragma unroll
;                 for (int q = 0; q < 8; ++q) { const f32x4 pv = *(const f32x4*)(rss + (size_t)row * 32 + 4 * q); rsum += (pv[0] + pv[1]) + (pv[2] + pv[3]); }
;                 const float rs = rsqrtf(rsum * (1.0f / (float)D) + EPS);
.LBB0_1527:
	s_or_b64 exec, exec, s[30:31]
	v_add_u32_e32 v82, 0x90, v176
	v_ashrrev_i32_e32 v83, 31, v82
	v_lshlrev_b64 v[48:49], 7, v[82:83]
	v_lshl_add_u64 v[60:61], s[0:1], 0, v[48:49]
	v_cmp_lt_i32_e32 vcc, s68, v176
	v_mov_b64_e32 v[80:81], 0
	s_and_saveexec_b64 s[30:31], vcc
	s_cbranch_execz .LBB0_1535
	v_cmp_lt_u32_e32 vcc, s63, v82
	s_and_saveexec_b64 s[34:35], vcc
	s_xor_b64 s[34:35], exec, s[34:35]
	s_cbranch_execz .LBB0_1532
	v_mov_b64_e32 v[80:81], 0
	s_and_saveexec_b64 s[36:37], s[4:5]
	s_add_i32 s25, s23, 0xffffc090
	s_lshr_b32 s25, s25, 3
	v_add_u32_e32 v83, s25, v189
	v_mov_b64_e32 v[80:81], s[10:11]
	v_mad_u64_u32 v[80:81], s[38:39], v83, s64, v[80:81]
	v_lshl_add_u64 v[80:81], v[174:175], 2, v[80:81]
	s_or_b64 exec, exec, s[36:37]

; __device__ __forceinline__ unsigned cvt_pk_bf16(float lo, float hi) { f32x2 v = {lo, hi}; bf16x2_t b = __builtin_convertvector(v, bf16x2_t); return __builtin_bit_cast(unsigned, b); }
;     __device__ __forceinline__ void operator()(const Acc& acc, const Unit& u, int wr, int wc, int fr, int fq) const {
;     ...
;                 float rsum = 0.f;
; #pragma unroll
;                 for (int q = 0; q < 8; ++q) { const f32x4 pv = *(const f32x4*)(rss + (size_t)row * 32 + 4 * q); rsum += (pv[0] + pv[1]) + (pv[2] + pv[3]); }
;                 const float rs = rsqrtf(rsum * (1.0f / (float)D) + EPS);
;                 float* co = nullptr;
;                 if (row >= MP - 2) { if (row < MP) co = out + O_CP + (size_t)(row - (MP - 2)) * DFF + col0;
;                                      else { const int t = (row - MP) & 15, b = (row - MP) >> 4; if (t >= 14) co = out + O_CS + (size_t)(b * 2 + t - 14) * DFF + col0; } }
; #pragma unroll
;                 for (int n = 0; n < 2; ++n) { const f32x4 z = acc[ai][0][m][n] * rs, v = acc[ai][1][m][n] * rs;
;                     u32x2 w; w.x = cvt_pk_bf16(z[0], z[1]); w.y = cvt_pk_bf16(z[2], z[3]); *(u32x2*)(Z + ro + 16 * n) = w;
;                     w.x = cvt_pk_bf16(v[0], v[1]); w.y = cvt_pk_bf16(v[2], v[3]); *(u32x2*)(VAL + ro + 16 * n) = w;
;                     if (co) *(f32x4*)(co + 16 * n) = z; } }
.LBB0_1535:
	s_or_b64 exec, exec, s[30:31]
	v_mad_i64_i32 v[50:51], s[30:31], v82, s65, v[174:175]
	v_mov_b32_e32 v48, v245
	v_fmamk_f32 v48, v48, 0x3a000000, v195
	v_mul_f32_e32 v49, 0x4b800000, v48
	v_cmp_gt_f32_e32 vcc, s66, v48
	v_lshlrev_b64 v[50:51], 1, v[50:51]
	s_nop 0
	v_cndmask_b32_e32 v48, v48, v49, vcc
	v_rsq_f32_e32 v48, v48
	s_nop 0
	v_mul_f32_e32 v49, 0x45800000, v48
	v_cndmask_b32_e32 v48, v48, v49, vcc
	v_pk_mul_f32 v[46:47], v[46:47], v[48:49] op_sel_hi:[1,0]
	v_pk_mul_f32 v[44:45], v[44:45], v[48:49] op_sel_hi:[1,0]
	v_pk_mul_f32 v[42:43], v[42:43], v[48:49] op_sel_hi:[1,0]
	v_pk_mul_f32 v[52:53], v[40:41], v[48:49] op_sel_hi:[1,0]
	v_cmp_ne_u64_e32 vcc, 0, v[80:81]
	v_cvt_pk_bf16_f32 v54, v44, v45
	v_cvt_pk_bf16_f32 v55, v46, v47
	v_lshl_add_u64 v[40:41], s[88:89], 0, v[50:51]
	v_cvt_pk_bf16_f32 v52, v52, v53
	v_cvt_pk_bf16_f32 v53, v42, v43
	v_lshl_add_u64 v[42:43], s[12:13], 0, v[50:51]
	global_store_dwordx2 v[40:41], v[54:55], off
	global_store_dwordx2 v[42:43], v[52:53], off
	s_and_saveexec_b64 s[30:31], vcc
	s_cbranch_execz .LBB0_1537
	global_store_dwordx4 v[80:81], v[44:47], off

;     __device__ __forceinline__ void operator()(const Acc& acc, const Unit& u, int wr, int wc, int fr, int fq) const {
;     ...
;             for (int m = 0; m < 4; ++m) { const int row = row0 + ai * HALF + m * 16; const size_t ro = (size_t)row * DFF + col0;
;                 float rsum = 0.f;
; #pragma unroll
;                 for (int q = 0; q < 8; ++q) { const f32x4 pv = *(const f32x4*)(rss + (size_t)row * 32 + 4 * q); rsum += (pv[0] + pv[1]) + (pv[2] + pv[3]); }
;                 const float rs = rsqrtf(rsum * (1.0f / (float)D) + EPS);
.LBB0_1539:
	s_or_b64 exec, exec, s[30:31]
	v_add_u32_e32 v66, 0xa0, v176
	v_ashrrev_i32_e32 v67, 31, v66
	v_lshlrev_b64 v[32:33], 7, v[66:67]
	v_lshl_add_u64 v[44:45], s[0:1], 0, v[32:33]
	v_cmp_lt_i32_e32 vcc, s69, v176
	v_mov_b64_e32 v[64:65], 0
	s_and_saveexec_b64 s[30:31], vcc
	s_cbranch_execz .LBB0_1547
	v_cmp_lt_u32_e32 vcc, s63, v66
	s_and_saveexec_b64 s[34:35], vcc
	s_xor_b64 s[34:35], exec, s[34:35]
	s_cbranch_execz .LBB0_1544
	v_mov_b64_e32 v[64:65], 0
	s_and_saveexec_b64 s[36:37], s[4:5]
	s_add_i32 s25, s23, 0xffffc0a0
	s_lshr_b32 s25, s25, 3
	v_add_u32_e32 v67, s25, v189
	v_mov_b64_e32 v[64:65], s[10:11]
	v_mad_u64_u32 v[64:65], s[38:39], v67, s64, v[64:65]
	v_lshl_add_u64 v[64:65], v[174:175], 2, v[64:65]
	s_or_b64 exec, exec, s[36:37]

; __device__ __forceinline__ unsigned cvt_pk_bf16(float lo, float hi) { f32x2 v = {lo, hi}; bf16x2_t b = __builtin_convertvector(v, bf16x2_t); return __builtin_bit_cast(unsigned, b); }
;     __device__ __forceinline__ void operator()(const Acc& acc, const Unit& u, int wr, int wc, int fr, int fq) const {
;     ...
;                 float rsum = 0.f;
; #pragma unroll
;                 for (int q = 0; q < 8; ++q) { const f32x4 pv = *(const f32x4*)(rss + (size_t)row * 32 + 4 * q); rsum += (pv[0] + pv[1]) + (pv[2] + pv[3]); }
;                 const float rs = rsqrtf(rsum * (1.0f / (float)D) + EPS);
;                 float* co = nullptr;
;                 if (row >= MP - 2) { if (row < MP) co = out + O_CP + (size_t)(row - (MP - 2)) * DFF + col0;
;                                      else { const int t = (row - MP) & 15, b = (row - MP) >> 4; if (t >= 14) co = out + O_CS + (size_t)(b * 2 + t - 14) * DFF + col0; } }
; #pragma unroll
;                 for (int n = 0; n < 2; ++n) { const f32x4 z = acc[ai][0][m][n] * rs, v = acc[ai][1][m][n] * rs;
;                     u32x2 w; w.x = cvt_pk_bf16(z[0], z[1]); w.y = cvt_pk_bf16(z[2], z[3]); *(u32x2*)(Z + ro + 16 * n) = w;
;                     w.x = cvt_pk_bf16(v[0], v[1]); w.y = cvt_pk_bf16(v[2], v[3]); *(u32x2*)(VAL + ro + 16 * n) = w;
;                     if (co) *(f32x4*)(co + 16 * n) = z; } }
.LBB0_1547:
	s_or_b64 exec, exec, s[30:31]
	v_mad_i64_i32 v[34:35], s[30:31], v66, s65, v[174:175]
	v_mov_b32_e32 v32, v246
	v_fmamk_f32 v32, v32, 0x3a000000, v195
	v_mul_f32_e32 v33, 0x4b800000, v32
	v_cmp_gt_f32_e32 vcc, s66, v32
	v_lshlrev_b64 v[34:35], 1, v[34:35]
	s_nop 0
	v_cndmask_b32_e32 v32, v32, v33, vcc
	v_rsq_f32_e32 v32, v32
	s_nop 0
	v_mul_f32_e32 v33, 0x45800000, v32
	v_cndmask_b32_e32 v32, v32, v33, vcc
	v_pk_mul_f32 v[30:31], v[30:31], v[32:33] op_sel_hi:[1,0]
	v_pk_mul_f32 v[28:29], v[28:29], v[32:33] op_sel_hi:[1,0]
	v_pk_mul_f32 v[26:27], v[26:27], v[32:33] op_sel_hi:[1,0]
	v_pk_mul_f32 v[36:37], v[24:25], v[32:33] op_sel_hi:[1,0]
	v_cmp_ne_u64_e32 vcc, 0, v[64:65]
	v_cvt_pk_bf16_f32 v38, v28, v29
	v_cvt_pk_bf16_f32 v39, v30, v31
	v_lshl_add_u64 v[24:25], s[88:89], 0, v[34:35]
	v_cvt_pk_bf16_f32 v36, v36, v37
	v_cvt_pk_bf16_f32 v37, v26, v27
	v_lshl_add_u64 v[26:27], s[12:13], 0, v[34:35]
	global_store_dwordx2 v[24:25], v[38:39], off
	global_store_dwordx2 v[26:27], v[36:37], off
	s_and_saveexec_b64 s[30:31], vcc
	s_cbranch_execz .LBB0_1549
	global_store_dwordx4 v[64:65], v[28:31], off

;     __device__ __forceinline__ void operator()(const Acc& acc, const Unit& u, int wr, int wc, int fr, int fq) const {
;     ...
;             for (int m = 0; m < 4; ++m) { const int row = row0 + ai * HALF + m * 16; const size_t ro = (size_t)row * DFF + col0;
;                 float rsum = 0.f;
; #pragma unroll
;                 for (int q = 0; q < 8; ++q) { const f32x4 pv = *(const f32x4*)(rss + (size_t)row * 32 + 4 * q); rsum += (pv[0] + pv[1]) + (pv[2] + pv[3]); }
;                 const float rs = rsqrtf(rsum * (1.0f / (float)D) + EPS);
.LBB0_1551:
	s_or_b64 exec, exec, s[30:31]
	v_add_u32_e32 v50, 0xb0, v176
	v_ashrrev_i32_e32 v51, 31, v50
	v_lshlrev_b64 v[16:17], 7, v[50:51]
	v_lshl_add_u64 v[28:29], s[0:1], 0, v[16:17]
	v_cmp_lt_i32_e32 vcc, s70, v176
	v_mov_b64_e32 v[48:49], 0
	s_and_saveexec_b64 s[30:31], vcc
	s_cbranch_execz .LBB0_1559
	v_cmp_lt_u32_e32 vcc, s63, v50
	s_and_saveexec_b64 s[34:35], vcc
	s_xor_b64 s[34:35], exec, s[34:35]
	s_cbranch_execz .LBB0_1556
	v_mov_b64_e32 v[48:49], 0
	s_and_saveexec_b64 s[36:37], s[4:5]
	s_addk_i32 s23, 0xc0b0
	s_lshr_b32 s23, s23, 3
	v_add_u32_e32 v51, s23, v189
	v_mov_b64_e32 v[48:49], s[10:11]
	v_mad_u64_u32 v[48:49], s[38:39], v51, s64, v[48:49]
	v_lshl_add_u64 v[48:49], v[174:175], 2, v[48:49]
	s_or_b64 exec, exec, s[36:37]

; __device__ __forceinline__ unsigned cvt_pk_bf16(float lo, float hi) { f32x2 v = {lo, hi}; bf16x2_t b = __builtin_convertvector(v, bf16x2_t); return __builtin_bit_cast(unsigned, b); }
;     __device__ __forceinline__ void operator()(const Acc& acc, const Unit& u, int wr, int wc, int fr, int fq) const {
;     ...
;                 float rsum = 0.f;
; #pragma unroll
;                 for (int q = 0; q < 8; ++q) { const f32x4 pv = *(const f32x4*)(rss + (size_t)row * 32 + 4 * q); rsum += (pv[0] + pv[1]) + (pv[2] + pv[3]); }
;                 const float rs = rsqrtf(rsum * (1.0f / (float)D) + EPS);
;                 float* co = nullptr;
;                 if (row >= MP - 2) { if (row < MP) co = out + O_CP + (size_t)(row - (MP - 2)) * DFF + col0;
;                                      else { const int t = (row - MP) & 15, b = (row - MP) >> 4; if (t >= 14) co = out + O_CS + (size_t)(b * 2 + t - 14) * DFF + col0; } }
; #pragma unroll
;                 for (int n = 0; n < 2; ++n) { const f32x4 z = acc[ai][0][m][n] * rs, v = acc[ai][1][m][n] * rs;
;                     u32x2 w; w.x = cvt_pk_bf16(z[0], z[1]); w.y = cvt_pk_bf16(z[2], z[3]); *(u32x2*)(Z + ro + 16 * n) = w;
;                     w.x = cvt_pk_bf16(v[0], v[1]); w.y = cvt_pk_bf16(v[2], v[3]); *(u32x2*)(VAL + ro + 16 * n) = w;
;                     if (co) *(f32x4*)(co + 16 * n) = z; } }
.LBB0_1559:
	s_or_b64 exec, exec, s[30:31]
	v_mad_i64_i32 v[18:19], s[30:31], v50, s65, v[174:175]
	v_mov_b32_e32 v16, v247
	v_fmamk_f32 v16, v16, 0x3a000000, v195
	v_mul_f32_e32 v17, 0x4b800000, v16
	v_cmp_gt_f32_e32 vcc, s66, v16
	v_lshlrev_b64 v[18:19], 1, v[18:19]
	s_nop 0
	v_cndmask_b32_e32 v16, v16, v17, vcc
	v_rsq_f32_e32 v16, v16
	s_nop 0
	v_mul_f32_e32 v17, 0x45800000, v16
	v_cndmask_b32_e32 v16, v16, v17, vcc
	v_pk_mul_f32 v[14:15], v[14:15], v[16:17] op_sel_hi:[1,0]
	v_pk_mul_f32 v[12:13], v[12:13], v[16:17] op_sel_hi:[1,0]
	v_pk_mul_f32 v[10:11], v[10:11], v[16:17] op_sel_hi:[1,0]
	v_pk_mul_f32 v[20:21], v[8:9], v[16:17] op_sel_hi:[1,0]
	v_cmp_ne_u64_e32 vcc, 0, v[48:49]
	v_cvt_pk_bf16_f32 v22, v12, v13
	v_cvt_pk_bf16_f32 v23, v14, v15
	v_lshl_add_u64 v[8:9], s[88:89], 0, v[18:19]
	v_cvt_pk_bf16_f32 v20, v20, v21
	v_cvt_pk_bf16_f32 v21, v10, v11
	v_lshl_add_u64 v[10:11], s[12:13], 0, v[18:19]
	global_store_dwordx2 v[8:9], v[22:23], off
	global_store_dwordx2 v[10:11], v[20:21], off
	s_and_saveexec_b64 s[30:31], vcc
	s_cbranch_execz .LBB0_1561
	global_store_dwordx4 v[48:49], v[12:15], off

; __global__ void __launch_bounds__(NWAVES * 64, 2) fwd_megakernel(Args a) {
	.amdhsa_kernel _Z14fwd_megakernel4Args
		.amdhsa_group_segment_fixed_size 0
		.amdhsa_private_segment_fixed_size 0
		.amdhsa_kernarg_size 480
		.amdhsa_user_sgpr_count 2
		.amdhsa_user_sgpr_dispatch_ptr 0
		.amdhsa_user_sgpr_queue_ptr 0
		.amdhsa_user_sgpr_kernarg_segment_ptr 1
		.amdhsa_user_sgpr_dispatch_id 0
		.amdhsa_user_sgpr_kernarg_preload_length 0
		.amdhsa_user_sgpr_kernarg_preload_offset 0
		.amdhsa_user_sgpr_private_segment_size 0
		.amdhsa_uses_dynamic_stack 0
		.amdhsa_enable_private_segment 0
		.amdhsa_system_sgpr_workgroup_id_x 1
		.amdhsa_system_sgpr_workgroup_id_y 0
		.amdhsa_system_sgpr_workgroup_id_z 0
		.amdhsa_system_sgpr_workgroup_info 0
		.amdhsa_system_vgpr_workitem_id 2
		.amdhsa_next_free_vgpr 256
		.amdhsa_next_free_sgpr 98
		.amdhsa_accum_offset 256
		.amdhsa_reserve_vcc 1
		.amdhsa_float_round_mode_32 0
		.amdhsa_float_round_mode_16_64 0
		.amdhsa_float_denorm_mode_32 3
		.amdhsa_float_denorm_mode_16_64 3
		.amdhsa_dx10_clamp 1
		.amdhsa_ieee_mode 1
		.amdhsa_fp16_overflow 0
		.amdhsa_tg_split 0
		.amdhsa_exception_fp_ieee_invalid_op 0
		.amdhsa_exception_fp_denorm_src 0
		.amdhsa_exception_fp_ieee_div_zero 0
		.amdhsa_exception_fp_ieee_overflow 0
		.amdhsa_exception_fp_ieee_underflow 0
		.amdhsa_exception_fp_ieee_inexact 0
		.amdhsa_exception_int_div_zero 0
	.end_amdhsa_kernel

; __global__ void __launch_bounds__(NWAVES * 64, 2) fwd_megakernel(Args a) {
amdhsa.kernels:
  - .agpr_count:     0
    .args:
      - .offset:         0
        .size:           224
        .value_kind:     by_value
      - .offset:         224
        .size:           4
        .value_kind:     hidden_block_count_x
      - .offset:         228
        .size:           4
        .value_kind:     hidden_block_count_y
      - .offset:         232
        .size:           4
        .value_kind:     hidden_block_count_z
      - .offset:         236
        .size:           2
        .value_kind:     hidden_group_size_x
      - .offset:         238
        .size:           2
        .value_kind:     hidden_group_size_y
      - .offset:         240
        .size:           2
        .value_kind:     hidden_group_size_z
      - .offset:         242
        .size:           2
        .value_kind:     hidden_remainder_x
      - .offset:         244
        .size:           2
        .value_kind:     hidden_remainder_y
      - .offset:         246
        .size:           2
        .value_kind:     hidden_remainder_z
      - .offset:         264
        .size:           8
        .value_kind:     hidden_global_offset_x
      - .offset:         272
        .size:           8
        .value_kind:     hidden_global_offset_y
      - .offset:         280
        .size:           8
        .value_kind:     hidden_global_offset_z
      - .offset:         288
        .size:           2
        .value_kind:     hidden_grid_dims
      - .offset:         312
        .size:           8
        .value_kind:     hidden_multigrid_sync_arg
      - .offset:         344
        .size:           4
        .value_kind:     hidden_dynamic_lds_size
    .group_segment_fixed_size: 0
    .kernarg_segment_align: 8
    .kernarg_segment_size: 480
    .language:       OpenCL C
    .language_version:
      - 2
      - 0
    .max_flat_workgroup_size: 512
    .name:           _Z14fwd_megakernel4Args
    .private_segment_fixed_size: 0
    .sgpr_count:     104
    .sgpr_spill_count: 28
    .symbol:         _Z14fwd_megakernel4Args.kd
    .uniform_work_group_size: 1
    .uses_dynamic_stack: false
    .vgpr_count:     256
    .vgpr_spill_count: 0
    .wavefront_size: 64
